# K-loop: Bs01 pair also deferred to LS1(t+1): DMA issue 4/2/6/4 over the four load segments (LS2(t) vmcnt 4)
# baseline (speedup 1.0000x reference)
.LBB0_178:
	s_add_u32 s82, s0, s80
	s_addc_u32 s83, s1, s81
	s_add_u32 s84, s82, 0x460000
	s_addc_u32 s85, s83, 0
	s_cmp_eq_u32 s80, 0x41a0000
	s_cselect_b64 s[86:87], -1, 0
	s_and_b64 s[82:83], s[86:87], exec
	s_cselect_b32 s83, s71, s97
	s_cselect_b32 s82, s73, s79
	s_mov_b32 m0, s9
	s_cselect_b32 s85, s22, s85
	s_cselect_b32 s84, s69, s84
	s_add_u32 vcc_lo, s82, 0x4000
	global_load_lds_dwordx4 v194, s[82:83]
	s_mov_b32 m0, s10
	s_addc_u32 vcc_hi, s83, 0
	global_load_lds_dwordx4 v196, s[82:83]
	s_nop 0
	s_and_b64 vcc, exec, s[48:49]
	s_mov_b64 s[98:99], s[84:85]
	s_waitcnt vmcnt(4) lgkmcnt(0)
	s_barrier
	s_cbranch_vccnz .LBB0_180
	s_waitcnt lgkmcnt(0)
	v_mfma_f32_16x16x32_bf16 v[54:57], v[146:149], v[174:177], v[54:57]
	v_mfma_f32_16x16x32_bf16 v[62:65], v[154:157], v[174:177], v[62:65]
	v_mfma_f32_16x16x32_bf16 v[38:41], v[146:149], v[170:173], v[38:41]
	v_mfma_f32_16x16x32_bf16 v[46:49], v[154:157], v[170:173], v[46:49]
	v_mfma_f32_16x16x32_bf16 v[22:25], v[146:149], v[166:169], v[22:25]
	v_mfma_f32_16x16x32_bf16 v[30:33], v[154:157], v[166:169], v[30:33]
	v_mfma_f32_16x16x32_bf16 v[10:13], v[146:149], v[162:165], v[10:13]
	v_mfma_f32_16x16x32_bf16 v[14:17], v[154:157], v[162:165], v[14:17]
	v_mfma_f32_16x16x32_bf16 v[54:57], v[150:153], v[190:193], v[54:57]
	v_mfma_f32_16x16x32_bf16 v[62:65], v[158:161], v[190:193], v[62:65]
	v_mfma_f32_16x16x32_bf16 v[38:41], v[150:153], v[186:189], v[38:41]
	v_mfma_f32_16x16x32_bf16 v[46:49], v[158:161], v[186:189], v[46:49]
	v_mfma_f32_16x16x32_bf16 v[22:25], v[150:153], v[182:185], v[22:25]
	v_mfma_f32_16x16x32_bf16 v[30:33], v[158:161], v[182:185], v[30:33]
	v_mfma_f32_16x16x32_bf16 v[10:13], v[150:153], v[178:181], v[10:13]
	v_mfma_f32_16x16x32_bf16 v[14:17], v[158:161], v[178:181], v[14:17]
	v_mfma_f32_16x16x32_bf16 v[58:61], v[130:133], v[174:177], v[58:61]
	v_mfma_f32_16x16x32_bf16 v[50:53], v[138:141], v[174:177], v[50:53]
	v_mfma_f32_16x16x32_bf16 v[42:45], v[130:133], v[170:173], v[42:45]
	v_mfma_f32_16x16x32_bf16 v[34:37], v[138:141], v[170:173], v[34:37]
	v_mfma_f32_16x16x32_bf16 v[26:29], v[130:133], v[166:169], v[26:29]
	v_mfma_f32_16x16x32_bf16 v[18:21], v[138:141], v[166:169], v[18:21]
	v_mfma_f32_16x16x32_bf16 v[6:9], v[130:133], v[162:165], v[6:9]
	v_mfma_f32_16x16x32_bf16 v[2:5], v[138:141], v[162:165], v[2:5]
	v_mfma_f32_16x16x32_bf16 v[58:61], v[134:137], v[190:193], v[58:61]
	v_mfma_f32_16x16x32_bf16 v[50:53], v[142:145], v[190:193], v[50:53]
	v_mfma_f32_16x16x32_bf16 v[42:45], v[134:137], v[186:189], v[42:45]
	v_mfma_f32_16x16x32_bf16 v[34:37], v[142:145], v[186:189], v[34:37]
	v_mfma_f32_16x16x32_bf16 v[26:29], v[134:137], v[182:185], v[26:29]
	v_mfma_f32_16x16x32_bf16 v[18:21], v[142:145], v[182:185], v[18:21]
	v_mfma_f32_16x16x32_bf16 v[6:9], v[134:137], v[178:181], v[6:9]
	v_mfma_f32_16x16x32_bf16 v[2:5], v[142:145], v[178:181], v[2:5]
.LBB0_180:
	s_and_b64 vcc, s[46:47], s[86:87]
	v_cndmask_b32_e64 v131, v233, 0, vcc
	v_cndmask_b32_e32 v130, v232, v198, vcc
	v_lshl_add_u64 v[246:247], s[84:85], 0, v[130:131]
	s_barrier
	s_mov_b32 m0, s8
	s_add_u32 vcc_lo, s82, 0x4000
	s_addc_u32 vcc_hi, s83, 0
	s_mov_b32 m0, s11
	s_nop 0
	global_load_lds_dwordx4 v194, vcc
	s_mov_b32 m0, s12
	s_nop 0
	global_load_lds_dwordx4 v196, vcc
	s_mov_b32 m0, s8
	s_nop 0
	global_load_lds_dwordx4 v194, s[98:99]
	s_mov_b32 m0, s13
	s_nop 0
	global_load_lds_dwordx4 v196, s[98:99]
	v_add_u32_e32 v130, 0x18000, v243
	v_add_u32_e32 v142, 0x1c000, v243
	ds_read_b128 v[146:149], v130
	ds_read_b128 v[150:153], v130 offset:1024
	ds_read_b128 v[154:157], v130 offset:2048
	ds_read_b128 v[158:161], v130 offset:3072
	ds_read_b128 v[130:133], v142
	ds_read_b128 v[134:137], v142 offset:1024
	ds_read_b128 v[138:141], v142 offset:2048
	ds_read_b128 v[142:145], v142 offset:3072
	s_mov_b32 m0, s14
	v_lshl_add_u64 v[248:249], v[246:247], 0, v[194:195]
	s_waitcnt lgkmcnt(0)
	ds_read_b128 v[174:177], v244 offset:32768
	ds_read_b128 v[190:193], v244 offset:33792
	ds_read_b128 v[170:173], v244 offset:34816
	ds_read_b128 v[186:189], v244 offset:35840
	ds_read_b128 v[166:169], v244 offset:36864
	ds_read_b128 v[182:185], v244 offset:37888
	ds_read_b128 v[162:165], v244 offset:38912
	ds_read_b128 v[178:181], v244 offset:39936
	global_load_lds_dwordx4 v[248:249], off
	v_lshl_add_u64 v[246:247], v[246:247], 0, v[196:197]
	s_mov_b32 m0, s15
	s_nop 0
	global_load_lds_dwordx4 v[246:247], off
	s_waitcnt vmcnt(8) lgkmcnt(0)
	s_barrier
	v_mfma_f32_16x16x32_bf16 v[118:121], v[146:149], v[174:177], v[118:121]
	v_mfma_f32_16x16x32_bf16 v[126:129], v[154:157], v[174:177], v[126:129]
	v_mfma_f32_16x16x32_bf16 v[102:105], v[146:149], v[170:173], v[102:105]
	v_mfma_f32_16x16x32_bf16 v[110:113], v[154:157], v[170:173], v[110:113]
	v_mfma_f32_16x16x32_bf16 v[86:89], v[146:149], v[166:169], v[86:89]
	v_mfma_f32_16x16x32_bf16 v[94:97], v[154:157], v[166:169], v[94:97]
	v_mfma_f32_16x16x32_bf16 v[70:73], v[146:149], v[162:165], v[70:73]
	v_mfma_f32_16x16x32_bf16 v[78:81], v[154:157], v[162:165], v[78:81]
	v_mfma_f32_16x16x32_bf16 v[118:121], v[150:153], v[190:193], v[118:121]
	v_mfma_f32_16x16x32_bf16 v[126:129], v[158:161], v[190:193], v[126:129]
	v_mfma_f32_16x16x32_bf16 v[102:105], v[150:153], v[186:189], v[102:105]
	v_mfma_f32_16x16x32_bf16 v[110:113], v[158:161], v[186:189], v[110:113]
	v_mfma_f32_16x16x32_bf16 v[86:89], v[150:153], v[182:185], v[86:89]
	v_mfma_f32_16x16x32_bf16 v[94:97], v[158:161], v[182:185], v[94:97]
	v_mfma_f32_16x16x32_bf16 v[70:73], v[150:153], v[178:181], v[70:73]
	v_mfma_f32_16x16x32_bf16 v[78:81], v[158:161], v[178:181], v[78:81]
	v_mfma_f32_16x16x32_bf16 v[122:125], v[130:133], v[174:177], v[122:125]
	v_mfma_f32_16x16x32_bf16 v[114:117], v[138:141], v[174:177], v[114:117]
	v_mfma_f32_16x16x32_bf16 v[106:109], v[130:133], v[170:173], v[106:109]
	v_mfma_f32_16x16x32_bf16 v[98:101], v[138:141], v[170:173], v[98:101]
	v_mfma_f32_16x16x32_bf16 v[90:93], v[130:133], v[166:169], v[90:93]
	v_mfma_f32_16x16x32_bf16 v[82:85], v[138:141], v[166:169], v[82:85]
	v_mfma_f32_16x16x32_bf16 v[74:77], v[130:133], v[162:165], v[74:77]
	v_mfma_f32_16x16x32_bf16 v[66:69], v[138:141], v[162:165], v[66:69]
	v_mfma_f32_16x16x32_bf16 v[122:125], v[134:137], v[190:193], v[122:125]
	v_mfma_f32_16x16x32_bf16 v[114:117], v[142:145], v[190:193], v[114:117]
	v_mfma_f32_16x16x32_bf16 v[106:109], v[134:137], v[186:189], v[106:109]
	v_mfma_f32_16x16x32_bf16 v[98:101], v[142:145], v[186:189], v[98:101]
	v_mfma_f32_16x16x32_bf16 v[90:93], v[134:137], v[182:185], v[90:93]
	v_mfma_f32_16x16x32_bf16 v[82:85], v[142:145], v[182:185], v[82:85]
	v_mfma_f32_16x16x32_bf16 v[74:77], v[134:137], v[178:181], v[74:77]
	v_mfma_f32_16x16x32_bf16 v[66:69], v[142:145], v[178:181], v[66:69]
	s_barrier
	s_and_b64 vcc, exec, s[48:49]
	s_cbranch_vccnz .LBB0_182
	ds_read_b128 v[174:177], v244 offset:49152
	ds_read_b128 v[190:193], v244 offset:50176
	ds_read_b128 v[170:173], v244 offset:51200
	ds_read_b128 v[186:189], v244 offset:52224
	ds_read_b128 v[166:169], v244 offset:53248
	ds_read_b128 v[182:185], v244 offset:54272
	ds_read_b128 v[162:165], v244 offset:55296
	ds_read_b128 v[178:181], v244 offset:56320

.LBB0_561:
	s_add_u32 s60, s56, s58
	s_addc_u32 s61, s57, s59
	s_add_u32 s62, s60, 0x440000
	s_addc_u32 s63, s61, 0
	s_cmp_eq_u32 s58, 0x3fc0000
	s_cselect_b64 s[68:69], -1, 0
	s_and_b64 s[60:61], s[68:69], exec
	s_cselect_b32 s61, s37, s72
	s_cselect_b32 s60, s47, s53
	s_mov_b32 m0, s9
	s_cselect_b32 s63, s1, s63
	s_cselect_b32 s62, s24, s62
	s_add_u32 s74, s60, 0x4000
	global_load_lds_dwordx4 v194, s[60:61]
	s_mov_b32 m0, s10
	s_addc_u32 s75, s61, 0
	global_load_lds_dwordx4 v196, s[60:61]
	s_and_b64 vcc, exec, s[42:43]
	s_nop 0
	s_mov_b64 s[98:99], s[62:63]
	s_waitcnt vmcnt(4) lgkmcnt(0)
	s_barrier
	s_cbranch_vccnz .LBB0_563
	s_waitcnt lgkmcnt(0)
	v_mfma_f32_16x16x32_bf16 v[62:65], v[146:149], v[174:177], v[62:65]
	v_mfma_f32_16x16x32_bf16 v[58:61], v[154:157], v[174:177], v[58:61]
	v_mfma_f32_16x16x32_bf16 v[46:49], v[146:149], v[170:173], v[46:49]
	v_mfma_f32_16x16x32_bf16 v[42:45], v[154:157], v[170:173], v[42:45]
	v_mfma_f32_16x16x32_bf16 v[30:33], v[146:149], v[166:169], v[30:33]
	v_mfma_f32_16x16x32_bf16 v[26:29], v[154:157], v[166:169], v[26:29]
	v_mfma_f32_16x16x32_bf16 v[14:17], v[146:149], v[162:165], v[14:17]
	v_mfma_f32_16x16x32_bf16 v[10:13], v[154:157], v[162:165], v[10:13]
	v_mfma_f32_16x16x32_bf16 v[62:65], v[150:153], v[190:193], v[62:65]
	v_mfma_f32_16x16x32_bf16 v[58:61], v[158:161], v[190:193], v[58:61]
	v_mfma_f32_16x16x32_bf16 v[46:49], v[150:153], v[186:189], v[46:49]
	v_mfma_f32_16x16x32_bf16 v[42:45], v[158:161], v[186:189], v[42:45]
	v_mfma_f32_16x16x32_bf16 v[30:33], v[150:153], v[182:185], v[30:33]
	v_mfma_f32_16x16x32_bf16 v[26:29], v[158:161], v[182:185], v[26:29]
	v_mfma_f32_16x16x32_bf16 v[14:17], v[150:153], v[178:181], v[14:17]
	v_mfma_f32_16x16x32_bf16 v[10:13], v[158:161], v[178:181], v[10:13]
	v_mfma_f32_16x16x32_bf16 v[54:57], v[130:133], v[174:177], v[54:57]
	v_mfma_f32_16x16x32_bf16 v[50:53], v[138:141], v[174:177], v[50:53]
	v_mfma_f32_16x16x32_bf16 v[38:41], v[130:133], v[170:173], v[38:41]
	v_mfma_f32_16x16x32_bf16 v[34:37], v[138:141], v[170:173], v[34:37]
	v_mfma_f32_16x16x32_bf16 v[22:25], v[130:133], v[166:169], v[22:25]
	v_mfma_f32_16x16x32_bf16 v[18:21], v[138:141], v[166:169], v[18:21]
	v_mfma_f32_16x16x32_bf16 v[6:9], v[130:133], v[162:165], v[6:9]
	v_mfma_f32_16x16x32_bf16 v[2:5], v[138:141], v[162:165], v[2:5]
	v_mfma_f32_16x16x32_bf16 v[54:57], v[134:137], v[190:193], v[54:57]
	v_mfma_f32_16x16x32_bf16 v[50:53], v[142:145], v[190:193], v[50:53]
	v_mfma_f32_16x16x32_bf16 v[38:41], v[134:137], v[186:189], v[38:41]
	v_mfma_f32_16x16x32_bf16 v[34:37], v[142:145], v[186:189], v[34:37]
	v_mfma_f32_16x16x32_bf16 v[22:25], v[134:137], v[182:185], v[22:25]
	v_mfma_f32_16x16x32_bf16 v[18:21], v[142:145], v[182:185], v[18:21]
	v_mfma_f32_16x16x32_bf16 v[6:9], v[134:137], v[178:181], v[6:9]
	v_mfma_f32_16x16x32_bf16 v[2:5], v[142:145], v[178:181], v[2:5]
.LBB0_563:
	s_and_b64 vcc, s[40:41], s[68:69]
	v_cndmask_b32_e64 v131, v215, 0, vcc
	v_cndmask_b32_e32 v130, v214, v198, vcc
	v_lshl_add_u64 v[234:235], s[62:63], 0, v[130:131]
	s_barrier
	s_mov_b32 m0, s8
	s_add_u32 vcc_lo, s60, 0x4000
	s_addc_u32 vcc_hi, s61, 0
	s_mov_b32 m0, s11
	s_nop 0
	global_load_lds_dwordx4 v194, vcc
	s_mov_b32 m0, s12
	s_nop 0
	global_load_lds_dwordx4 v196, vcc
	s_mov_b32 m0, s8
	s_nop 0
	global_load_lds_dwordx4 v194, s[98:99]
	s_mov_b32 m0, s13
	s_nop 0
	global_load_lds_dwordx4 v196, s[98:99]
	v_add_u32_e32 v130, 0x18000, v226
	v_add_u32_e32 v142, 0x1c000, v226
	ds_read_b128 v[146:149], v130
	ds_read_b128 v[150:153], v130 offset:1024
	ds_read_b128 v[154:157], v130 offset:2048
	ds_read_b128 v[158:161], v130 offset:3072
	ds_read_b128 v[130:133], v142
	ds_read_b128 v[134:137], v142 offset:1024
	ds_read_b128 v[138:141], v142 offset:2048
	ds_read_b128 v[142:145], v142 offset:3072
	s_mov_b32 m0, s14
	v_lshl_add_u64 v[236:237], v[234:235], 0, v[194:195]
	s_waitcnt lgkmcnt(0)
	ds_read_b128 v[174:177], v229 offset:32768
	ds_read_b128 v[190:193], v229 offset:33792
	ds_read_b128 v[170:173], v229 offset:34816
	ds_read_b128 v[186:189], v229 offset:35840
	ds_read_b128 v[166:169], v229 offset:36864
	ds_read_b128 v[182:185], v229 offset:37888
	ds_read_b128 v[162:165], v229 offset:38912
	ds_read_b128 v[178:181], v229 offset:39936
	global_load_lds_dwordx4 v[236:237], off
	v_lshl_add_u64 v[234:235], v[234:235], 0, v[196:197]
	s_mov_b32 m0, s15
	s_nop 0
	global_load_lds_dwordx4 v[234:235], off
	s_waitcnt vmcnt(8) lgkmcnt(0)
	s_barrier
	v_mfma_f32_16x16x32_bf16 v[126:129], v[146:149], v[174:177], v[126:129]
	v_mfma_f32_16x16x32_bf16 v[122:125], v[154:157], v[174:177], v[122:125]
	v_mfma_f32_16x16x32_bf16 v[110:113], v[146:149], v[170:173], v[110:113]
	v_mfma_f32_16x16x32_bf16 v[106:109], v[154:157], v[170:173], v[106:109]
	v_mfma_f32_16x16x32_bf16 v[94:97], v[146:149], v[166:169], v[94:97]
	v_mfma_f32_16x16x32_bf16 v[90:93], v[154:157], v[166:169], v[90:93]
	v_mfma_f32_16x16x32_bf16 v[78:81], v[146:149], v[162:165], v[78:81]
	v_mfma_f32_16x16x32_bf16 v[74:77], v[154:157], v[162:165], v[74:77]
	v_mfma_f32_16x16x32_bf16 v[126:129], v[150:153], v[190:193], v[126:129]
	v_mfma_f32_16x16x32_bf16 v[122:125], v[158:161], v[190:193], v[122:125]
	v_mfma_f32_16x16x32_bf16 v[110:113], v[150:153], v[186:189], v[110:113]
	v_mfma_f32_16x16x32_bf16 v[106:109], v[158:161], v[186:189], v[106:109]
	v_mfma_f32_16x16x32_bf16 v[94:97], v[150:153], v[182:185], v[94:97]
	v_mfma_f32_16x16x32_bf16 v[90:93], v[158:161], v[182:185], v[90:93]
	v_mfma_f32_16x16x32_bf16 v[78:81], v[150:153], v[178:181], v[78:81]
	v_mfma_f32_16x16x32_bf16 v[74:77], v[158:161], v[178:181], v[74:77]
	v_mfma_f32_16x16x32_bf16 v[118:121], v[130:133], v[174:177], v[118:121]
	v_mfma_f32_16x16x32_bf16 v[114:117], v[138:141], v[174:177], v[114:117]
	v_mfma_f32_16x16x32_bf16 v[102:105], v[130:133], v[170:173], v[102:105]
	v_mfma_f32_16x16x32_bf16 v[98:101], v[138:141], v[170:173], v[98:101]
	v_mfma_f32_16x16x32_bf16 v[86:89], v[130:133], v[166:169], v[86:89]
	v_mfma_f32_16x16x32_bf16 v[82:85], v[138:141], v[166:169], v[82:85]
	v_mfma_f32_16x16x32_bf16 v[70:73], v[130:133], v[162:165], v[70:73]
	v_mfma_f32_16x16x32_bf16 v[66:69], v[138:141], v[162:165], v[66:69]
	v_mfma_f32_16x16x32_bf16 v[118:121], v[134:137], v[190:193], v[118:121]
	v_mfma_f32_16x16x32_bf16 v[114:117], v[142:145], v[190:193], v[114:117]
	v_mfma_f32_16x16x32_bf16 v[102:105], v[134:137], v[186:189], v[102:105]
	v_mfma_f32_16x16x32_bf16 v[98:101], v[142:145], v[186:189], v[98:101]
	v_mfma_f32_16x16x32_bf16 v[86:89], v[134:137], v[182:185], v[86:89]
	v_mfma_f32_16x16x32_bf16 v[82:85], v[142:145], v[182:185], v[82:85]
	v_mfma_f32_16x16x32_bf16 v[70:73], v[134:137], v[178:181], v[70:73]
	v_mfma_f32_16x16x32_bf16 v[66:69], v[142:145], v[178:181], v[66:69]
	s_barrier
	s_and_b64 vcc, exec, s[42:43]
	s_cbranch_vccnz .LBB0_565
	ds_read_b128 v[174:177], v229 offset:49152
	ds_read_b128 v[190:193], v229 offset:50176
	ds_read_b128 v[170:173], v229 offset:51200
	ds_read_b128 v[186:189], v229 offset:52224
	ds_read_b128 v[166:169], v229 offset:53248
	ds_read_b128 v[182:185], v229 offset:54272
	ds_read_b128 v[162:165], v229 offset:55296
	ds_read_b128 v[178:181], v229 offset:56320

.LBB0_761:
	s_mov_b32 m0, s14
	s_nop 0
	global_load_lds_dwordx4 v194, s[100:101]
	s_mov_b32 m0, s15
	s_nop 0
	global_load_lds_dwordx4 v196, s[100:101]
	ds_read_b128 v[130:133], v237
	ds_read_b128 v[134:137], v237 offset:1024
	ds_read_b128 v[138:141], v237 offset:2048
	ds_read_b128 v[142:145], v237 offset:3072
	ds_read_b128 v[146:149], v238
	ds_read_b128 v[150:153], v238 offset:1024
	ds_read_b128 v[154:157], v238 offset:2048
	ds_read_b128 v[158:161], v238 offset:3072
	s_add_u32 s48, s0, 0x21c000
	s_addc_u32 s49, s1, 0
	s_cmp_eq_u32 s67, 28
	s_cselect_b32 s42, s55, s62
	s_cselect_b32 s43, s29, s63
	s_cselect_b32 s52, s45, s48
	s_cselect_b32 s53, s31, s49
	s_add_u32 s50, s42, 0xe0000
	s_addc_u32 s51, s43, 0
	s_add_u32 s48, s52, 0x220000
	s_addc_u32 s49, s53, 0
	v_lshl_add_u64 v[208:209], s[0:1], 0, v[202:203]
	s_add_i32 m0, s9, 0xc000
	ds_read_b128 v[162:165], v239
	ds_read_b128 v[166:169], v239 offset:1024
	ds_read_b128 v[170:173], v239 offset:2048
	ds_read_b128 v[174:177], v239 offset:3072
	ds_read_b128 v[178:181], v239 offset:4096
	ds_read_b128 v[182:185], v239 offset:5120
	ds_read_b128 v[186:189], v239 offset:6144
	ds_read_b128 v[190:193], v239 offset:7168
	global_load_lds_dwordx4 v[208:209], off
	v_lshl_add_u64 v[208:209], s[0:1], 0, v[200:201]
	s_add_i32 m0, s9, 0xe000
	s_nop 0
	global_load_lds_dwordx4 v[208:209], off
	s_waitcnt vmcnt(8) lgkmcnt(0)
	s_barrier
	v_mfma_f32_16x16x32_bf16 v[126:129], v[130:133], v[162:165], v[126:129]
	v_mfma_f32_16x16x32_bf16 v[122:125], v[138:141], v[162:165], v[122:125]
	v_mfma_f32_16x16x32_bf16 v[118:121], v[130:133], v[170:173], v[118:121]
	v_mfma_f32_16x16x32_bf16 v[114:117], v[138:141], v[170:173], v[114:117]
	v_mfma_f32_16x16x32_bf16 v[110:113], v[130:133], v[178:181], v[110:113]
	v_mfma_f32_16x16x32_bf16 v[106:109], v[138:141], v[178:181], v[106:109]
	v_mfma_f32_16x16x32_bf16 v[102:105], v[130:133], v[186:189], v[102:105]
	v_mfma_f32_16x16x32_bf16 v[98:101], v[138:141], v[186:189], v[98:101]
	v_mfma_f32_16x16x32_bf16 v[126:129], v[134:137], v[166:169], v[126:129]
	v_mfma_f32_16x16x32_bf16 v[122:125], v[142:145], v[166:169], v[122:125]
	v_mfma_f32_16x16x32_bf16 v[118:121], v[134:137], v[174:177], v[118:121]
	v_mfma_f32_16x16x32_bf16 v[114:117], v[142:145], v[174:177], v[114:117]
	v_mfma_f32_16x16x32_bf16 v[110:113], v[134:137], v[182:185], v[110:113]
	v_mfma_f32_16x16x32_bf16 v[106:109], v[142:145], v[182:185], v[106:109]
	v_mfma_f32_16x16x32_bf16 v[102:105], v[134:137], v[190:193], v[102:105]
	v_mfma_f32_16x16x32_bf16 v[98:101], v[142:145], v[190:193], v[98:101]
	v_mfma_f32_16x16x32_bf16 v[62:65], v[146:149], v[162:165], v[62:65]
	s_add_u32 s60, s52, 0x4000
	s_addc_u32 s61, s53, 0
	v_mfma_f32_16x16x32_bf16 v[58:61], v[154:157], v[162:165], v[58:61]
	v_mfma_f32_16x16x32_bf16 v[54:57], v[146:149], v[170:173], v[54:57]
	v_mfma_f32_16x16x32_bf16 v[50:53], v[154:157], v[170:173], v[50:53]
	v_mfma_f32_16x16x32_bf16 v[46:49], v[146:149], v[178:181], v[46:49]
	v_mfma_f32_16x16x32_bf16 v[42:45], v[154:157], v[178:181], v[42:45]
	v_mfma_f32_16x16x32_bf16 v[38:41], v[146:149], v[186:189], v[38:41]
	v_mfma_f32_16x16x32_bf16 v[34:37], v[154:157], v[186:189], v[34:37]
	v_mfma_f32_16x16x32_bf16 v[62:65], v[150:153], v[166:169], v[62:65]
	v_mfma_f32_16x16x32_bf16 v[58:61], v[158:161], v[166:169], v[58:61]
	v_mfma_f32_16x16x32_bf16 v[54:57], v[150:153], v[174:177], v[54:57]
	v_mfma_f32_16x16x32_bf16 v[50:53], v[158:161], v[174:177], v[50:53]
	v_mfma_f32_16x16x32_bf16 v[46:49], v[150:153], v[182:185], v[46:49]
	v_mfma_f32_16x16x32_bf16 v[42:45], v[158:161], v[182:185], v[42:45]
	v_mfma_f32_16x16x32_bf16 v[38:41], v[150:153], v[190:193], v[38:41]
	v_mfma_f32_16x16x32_bf16 v[34:37], v[158:161], v[190:193], v[34:37]
	s_barrier
	s_add_i32 s68, s16, s8
	s_mov_b32 m0, s68
	ds_read_b128 v[162:165], v239 offset:16384
	ds_read_b128 v[166:169], v239 offset:17408
	ds_read_b128 v[170:173], v239 offset:18432
	ds_read_b128 v[174:177], v239 offset:19456
	ds_read_b128 v[178:181], v239 offset:20480
	ds_read_b128 v[182:185], v239 offset:21504
	ds_read_b128 v[186:189], v239 offset:22528
	ds_read_b128 v[190:193], v239 offset:23552
	global_load_lds_dwordx4 v194, s[42:43]
	s_add_i32 m0, s68, 0x2000
	s_add_u32 s68, s42, 0x4000
	s_addc_u32 s69, s43, 0
	s_add_i32 s70, s17, s8
	global_load_lds_dwordx4 v196, s[42:43]
	s_nop 0
	s_nop 0
	s_mov_b64 s[98:99], s[52:53]
	s_waitcnt vmcnt(4) lgkmcnt(0)
	s_barrier
	v_mfma_f32_16x16x32_bf16 v[94:97], v[130:133], v[162:165], v[94:97]
	v_mfma_f32_16x16x32_bf16 v[90:93], v[138:141], v[162:165], v[90:93]
	v_mfma_f32_16x16x32_bf16 v[86:89], v[130:133], v[170:173], v[86:89]
	v_mfma_f32_16x16x32_bf16 v[82:85], v[138:141], v[170:173], v[82:85]
	v_mfma_f32_16x16x32_bf16 v[78:81], v[130:133], v[178:181], v[78:81]
	v_mfma_f32_16x16x32_bf16 v[74:77], v[138:141], v[178:181], v[74:77]
	v_mfma_f32_16x16x32_bf16 v[70:73], v[130:133], v[186:189], v[70:73]
	v_mfma_f32_16x16x32_bf16 v[66:69], v[138:141], v[186:189], v[66:69]
	v_mfma_f32_16x16x32_bf16 v[94:97], v[134:137], v[166:169], v[94:97]
	v_mfma_f32_16x16x32_bf16 v[90:93], v[142:145], v[166:169], v[90:93]
	v_mfma_f32_16x16x32_bf16 v[86:89], v[134:137], v[174:177], v[86:89]
	v_mfma_f32_16x16x32_bf16 v[82:85], v[142:145], v[174:177], v[82:85]
	v_mfma_f32_16x16x32_bf16 v[78:81], v[134:137], v[182:185], v[78:81]
	v_mfma_f32_16x16x32_bf16 v[74:77], v[142:145], v[182:185], v[74:77]
	v_mfma_f32_16x16x32_bf16 v[70:73], v[134:137], v[190:193], v[70:73]
	v_mfma_f32_16x16x32_bf16 v[66:69], v[142:145], v[190:193], v[66:69]
	v_mfma_f32_16x16x32_bf16 v[30:33], v[146:149], v[162:165], v[30:33]
	v_mfma_f32_16x16x32_bf16 v[26:29], v[154:157], v[162:165], v[26:29]
	v_mfma_f32_16x16x32_bf16 v[22:25], v[146:149], v[170:173], v[22:25]
	v_mfma_f32_16x16x32_bf16 v[18:21], v[154:157], v[170:173], v[18:21]
	v_mfma_f32_16x16x32_bf16 v[14:17], v[146:149], v[178:181], v[14:17]
	v_mfma_f32_16x16x32_bf16 v[10:13], v[154:157], v[178:181], v[10:13]
	v_mfma_f32_16x16x32_bf16 v[6:9], v[146:149], v[186:189], v[6:9]
	v_mfma_f32_16x16x32_bf16 v[2:5], v[154:157], v[186:189], v[2:5]
	v_mfma_f32_16x16x32_bf16 v[30:33], v[150:153], v[166:169], v[30:33]
	v_mfma_f32_16x16x32_bf16 v[26:29], v[158:161], v[166:169], v[26:29]
	v_mfma_f32_16x16x32_bf16 v[22:25], v[150:153], v[174:177], v[22:25]
	v_mfma_f32_16x16x32_bf16 v[18:21], v[158:161], v[174:177], v[18:21]
	v_mfma_f32_16x16x32_bf16 v[14:17], v[150:153], v[182:185], v[14:17]
	v_mfma_f32_16x16x32_bf16 v[10:13], v[158:161], v[182:185], v[10:13]
	v_mfma_f32_16x16x32_bf16 v[6:9], v[150:153], v[190:193], v[6:9]
	v_mfma_f32_16x16x32_bf16 v[2:5], v[158:161], v[190:193], v[2:5]
	s_barrier
	s_mov_b32 m0, s9
	s_add_u32 vcc_lo, s42, 0x4000
	s_addc_u32 vcc_hi, s43, 0
	s_mov_b32 m0, s70
	s_nop 0
	global_load_lds_dwordx4 v194, vcc
	s_add_i32 m0, s70, 0x2000
	s_nop 0
	global_load_lds_dwordx4 v196, vcc
	s_mov_b32 m0, s9
	s_nop 0
	global_load_lds_dwordx4 v194, s[98:99]
	s_mov_b32 m0, s10
	s_nop 0
	global_load_lds_dwordx4 v196, s[98:99]
	s_add_i32 s52, 0, 0x18000
	s_add_i32 s53, 0, 0x1c000
	v_add_u32_e32 v142, s52, v228
	v_add_u32_e32 v158, s53, v228
	ds_read_b128 v[130:133], v142
	ds_read_b128 v[134:137], v142 offset:1024
	ds_read_b128 v[138:141], v142 offset:2048
	ds_read_b128 v[142:145], v142 offset:3072
	ds_read_b128 v[146:149], v158
	ds_read_b128 v[150:153], v158 offset:1024
	ds_read_b128 v[154:157], v158 offset:2048
	ds_read_b128 v[158:161], v158 offset:3072
	s_mov_b32 m0, s11
	ds_read_b128 v[162:165], v239 offset:32768
	ds_read_b128 v[166:169], v239 offset:33792
	ds_read_b128 v[170:173], v239 offset:34816
	ds_read_b128 v[174:177], v239 offset:35840
	ds_read_b128 v[178:181], v239 offset:36864
	ds_read_b128 v[182:185], v239 offset:37888
	ds_read_b128 v[186:189], v239 offset:38912
	ds_read_b128 v[190:193], v239 offset:39936
	global_load_lds_dwordx4 v194, s[60:61]
	s_mov_b32 m0, s12
	s_nop 0
	global_load_lds_dwordx4 v196, s[60:61]
	s_waitcnt vmcnt(8) lgkmcnt(0)
	s_barrier
	v_mfma_f32_16x16x32_bf16 v[126:129], v[130:133], v[162:165], v[126:129]
	v_mfma_f32_16x16x32_bf16 v[122:125], v[138:141], v[162:165], v[122:125]
	v_mfma_f32_16x16x32_bf16 v[118:121], v[130:133], v[170:173], v[118:121]
	v_mfma_f32_16x16x32_bf16 v[114:117], v[138:141], v[170:173], v[114:117]
	v_mfma_f32_16x16x32_bf16 v[110:113], v[130:133], v[178:181], v[110:113]
	v_mfma_f32_16x16x32_bf16 v[106:109], v[138:141], v[178:181], v[106:109]
	v_mfma_f32_16x16x32_bf16 v[102:105], v[130:133], v[186:189], v[102:105]
	v_mfma_f32_16x16x32_bf16 v[98:101], v[138:141], v[186:189], v[98:101]
	v_mfma_f32_16x16x32_bf16 v[126:129], v[134:137], v[166:169], v[126:129]
	v_mfma_f32_16x16x32_bf16 v[122:125], v[142:145], v[166:169], v[122:125]
	v_mfma_f32_16x16x32_bf16 v[118:121], v[134:137], v[174:177], v[118:121]
	v_mfma_f32_16x16x32_bf16 v[114:117], v[142:145], v[174:177], v[114:117]
	v_mfma_f32_16x16x32_bf16 v[110:113], v[134:137], v[182:185], v[110:113]
	v_mfma_f32_16x16x32_bf16 v[106:109], v[142:145], v[182:185], v[106:109]
	v_mfma_f32_16x16x32_bf16 v[102:105], v[134:137], v[190:193], v[102:105]
	v_mfma_f32_16x16x32_bf16 v[98:101], v[142:145], v[190:193], v[98:101]
	v_mfma_f32_16x16x32_bf16 v[62:65], v[146:149], v[162:165], v[62:65]
	v_mfma_f32_16x16x32_bf16 v[58:61], v[154:157], v[162:165], v[58:61]
	v_mfma_f32_16x16x32_bf16 v[54:57], v[146:149], v[170:173], v[54:57]
	v_mfma_f32_16x16x32_bf16 v[50:53], v[154:157], v[170:173], v[50:53]
	v_mfma_f32_16x16x32_bf16 v[46:49], v[146:149], v[178:181], v[46:49]
	v_mfma_f32_16x16x32_bf16 v[42:45], v[154:157], v[178:181], v[42:45]
	v_mfma_f32_16x16x32_bf16 v[38:41], v[146:149], v[186:189], v[38:41]
	v_mfma_f32_16x16x32_bf16 v[34:37], v[154:157], v[186:189], v[34:37]
	v_mfma_f32_16x16x32_bf16 v[62:65], v[150:153], v[166:169], v[62:65]
	v_mfma_f32_16x16x32_bf16 v[58:61], v[158:161], v[166:169], v[58:61]
	v_mfma_f32_16x16x32_bf16 v[54:57], v[150:153], v[174:177], v[54:57]
	v_mfma_f32_16x16x32_bf16 v[50:53], v[158:161], v[174:177], v[50:53]
	v_mfma_f32_16x16x32_bf16 v[46:49], v[150:153], v[182:185], v[46:49]
	v_mfma_f32_16x16x32_bf16 v[42:45], v[158:161], v[182:185], v[42:45]
	v_mfma_f32_16x16x32_bf16 v[38:41], v[150:153], v[190:193], v[38:41]
	v_mfma_f32_16x16x32_bf16 v[34:37], v[158:161], v[190:193], v[34:37]
	s_barrier
	s_add_i32 s52, s52, s8
	s_mov_b32 m0, s52
	ds_read_b128 v[162:165], v239 offset:49152
	ds_read_b128 v[166:169], v239 offset:50176
	ds_read_b128 v[170:173], v239 offset:51200
	ds_read_b128 v[174:177], v239 offset:52224
	ds_read_b128 v[178:181], v239 offset:53248
	ds_read_b128 v[182:185], v239 offset:54272
	ds_read_b128 v[186:189], v239 offset:55296
	ds_read_b128 v[190:193], v239 offset:56320
	global_load_lds_dwordx4 v194, s[50:51]
	s_add_i32 m0, s52, 0x2000
	s_add_u32 s42, s42, 0xe4000
	v_lshl_add_u64 v[208:209], s[50:51], 0, v[196:197]
	s_addc_u32 s43, s43, 0
	s_add_i32 s50, s53, s8
	global_load_lds_dwordx4 v[208:209], off
	s_mov_b32 m0, s50
	s_nop 0
	global_load_lds_dwordx4 v194, s[42:43]
	s_add_i32 m0, s50, 0x2000
	s_nop 0
	global_load_lds_dwordx4 v196, s[42:43]
	s_mov_b64 s[100:101], s[48:49]
	s_waitcnt vmcnt(6) lgkmcnt(0)
	s_barrier
	v_mfma_f32_16x16x32_bf16 v[94:97], v[130:133], v[162:165], v[94:97]
	v_mfma_f32_16x16x32_bf16 v[90:93], v[138:141], v[162:165], v[90:93]
	v_mfma_f32_16x16x32_bf16 v[86:89], v[130:133], v[170:173], v[86:89]
	v_mfma_f32_16x16x32_bf16 v[82:85], v[138:141], v[170:173], v[82:85]
	v_mfma_f32_16x16x32_bf16 v[78:81], v[130:133], v[178:181], v[78:81]
	v_mfma_f32_16x16x32_bf16 v[74:77], v[138:141], v[178:181], v[74:77]
	v_mfma_f32_16x16x32_bf16 v[70:73], v[130:133], v[186:189], v[70:73]
	v_mfma_f32_16x16x32_bf16 v[66:69], v[138:141], v[186:189], v[66:69]
	v_mfma_f32_16x16x32_bf16 v[94:97], v[134:137], v[166:169], v[94:97]
	v_mfma_f32_16x16x32_bf16 v[90:93], v[142:145], v[166:169], v[90:93]
	v_mfma_f32_16x16x32_bf16 v[86:89], v[134:137], v[174:177], v[86:89]
	v_mfma_f32_16x16x32_bf16 v[82:85], v[142:145], v[174:177], v[82:85]
	v_mfma_f32_16x16x32_bf16 v[78:81], v[134:137], v[182:185], v[78:81]
	v_mfma_f32_16x16x32_bf16 v[74:77], v[142:145], v[182:185], v[74:77]
	v_mfma_f32_16x16x32_bf16 v[70:73], v[134:137], v[190:193], v[70:73]
	v_mfma_f32_16x16x32_bf16 v[66:69], v[142:145], v[190:193], v[66:69]
	v_mfma_f32_16x16x32_bf16 v[30:33], v[146:149], v[162:165], v[30:33]
	v_mfma_f32_16x16x32_bf16 v[26:29], v[154:157], v[162:165], v[26:29]
	v_mfma_f32_16x16x32_bf16 v[22:25], v[146:149], v[170:173], v[22:25]
	v_mfma_f32_16x16x32_bf16 v[18:21], v[154:157], v[170:173], v[18:21]
	v_mfma_f32_16x16x32_bf16 v[14:17], v[146:149], v[178:181], v[14:17]
	v_mfma_f32_16x16x32_bf16 v[10:13], v[154:157], v[178:181], v[10:13]
	v_mfma_f32_16x16x32_bf16 v[6:9], v[146:149], v[186:189], v[6:9]
	v_mfma_f32_16x16x32_bf16 v[2:5], v[154:157], v[186:189], v[2:5]
	v_mfma_f32_16x16x32_bf16 v[30:33], v[150:153], v[166:169], v[30:33]
	v_mfma_f32_16x16x32_bf16 v[26:29], v[158:161], v[166:169], v[26:29]
	v_mfma_f32_16x16x32_bf16 v[22:25], v[150:153], v[174:177], v[22:25]
	v_mfma_f32_16x16x32_bf16 v[18:21], v[158:161], v[174:177], v[18:21]
	v_mfma_f32_16x16x32_bf16 v[14:17], v[150:153], v[182:185], v[14:17]
	v_mfma_f32_16x16x32_bf16 v[10:13], v[158:161], v[182:185], v[10:13]
	v_mfma_f32_16x16x32_bf16 v[6:9], v[150:153], v[190:193], v[6:9]
	v_mfma_f32_16x16x32_bf16 v[2:5], v[158:161], v[190:193], v[2:5]
	s_barrier
	s_add_i32 s67, s67, 2
	s_add_u32 s62, s62, 0x1c0000
	s_addc_u32 s63, s63, 0
	s_add_u32 s0, s0, 0x440000
	s_addc_u32 s1, s1, 0
	s_cmp_gt_u32 s67, 29
	s_cbranch_scc0 .LBB0_761
	s_and_b64 vcc, exec, s[26:27]
	s_cbranch_vccz .LBB0_764
	s_barrier

.LBB0_905:
	s_add_u32 s68, s0, s62
	s_addc_u32 s69, s1, s63
	s_add_u32 s70, s68, 0x440000
	s_addc_u32 s71, s69, 0
	s_cmp_eq_u32 s62, 0x3fc0000
	s_cselect_b64 s[72:73], -1, 0
	s_and_b64 s[68:69], s[72:73], exec
	s_cselect_b32 s69, s37, s77
	s_cselect_b32 s68, s75, s76
	s_mov_b32 m0, s9
	s_cselect_b32 s71, s35, s71
	s_cselect_b32 s70, s74, s70
	s_add_u32 s80, s68, 0x4000
	global_load_lds_dwordx4 v194, s[68:69]
	s_mov_b32 m0, s10
	s_addc_u32 s81, s69, 0
	global_load_lds_dwordx4 v196, s[68:69]
	s_and_b64 vcc, exec, s[42:43]
	s_nop 0
	s_mov_b64 s[98:99], s[70:71]
	s_waitcnt vmcnt(4) lgkmcnt(0)
	s_barrier
	s_cbranch_vccnz .LBB0_907
	s_waitcnt lgkmcnt(0)
	v_mfma_f32_16x16x32_bf16 v[62:65], v[146:149], v[174:177], v[62:65]
	v_mfma_f32_16x16x32_bf16 v[58:61], v[154:157], v[174:177], v[58:61]
	v_mfma_f32_16x16x32_bf16 v[54:57], v[146:149], v[170:173], v[54:57]
	v_mfma_f32_16x16x32_bf16 v[50:53], v[154:157], v[170:173], v[50:53]
	v_mfma_f32_16x16x32_bf16 v[46:49], v[146:149], v[166:169], v[46:49]
	v_mfma_f32_16x16x32_bf16 v[42:45], v[154:157], v[166:169], v[42:45]
	v_mfma_f32_16x16x32_bf16 v[38:41], v[146:149], v[162:165], v[38:41]
	v_mfma_f32_16x16x32_bf16 v[34:37], v[154:157], v[162:165], v[34:37]
	v_mfma_f32_16x16x32_bf16 v[62:65], v[150:153], v[190:193], v[62:65]
	v_mfma_f32_16x16x32_bf16 v[58:61], v[158:161], v[190:193], v[58:61]
	v_mfma_f32_16x16x32_bf16 v[54:57], v[150:153], v[186:189], v[54:57]
	v_mfma_f32_16x16x32_bf16 v[50:53], v[158:161], v[186:189], v[50:53]
	v_mfma_f32_16x16x32_bf16 v[46:49], v[150:153], v[182:185], v[46:49]
	v_mfma_f32_16x16x32_bf16 v[42:45], v[158:161], v[182:185], v[42:45]
	v_mfma_f32_16x16x32_bf16 v[38:41], v[150:153], v[178:181], v[38:41]
	v_mfma_f32_16x16x32_bf16 v[34:37], v[158:161], v[178:181], v[34:37]
	v_mfma_f32_16x16x32_bf16 v[30:33], v[130:133], v[174:177], v[30:33]
	v_mfma_f32_16x16x32_bf16 v[26:29], v[138:141], v[174:177], v[26:29]
	v_mfma_f32_16x16x32_bf16 v[22:25], v[130:133], v[170:173], v[22:25]
	v_mfma_f32_16x16x32_bf16 v[18:21], v[138:141], v[170:173], v[18:21]
	v_mfma_f32_16x16x32_bf16 v[14:17], v[130:133], v[166:169], v[14:17]
	v_mfma_f32_16x16x32_bf16 v[10:13], v[138:141], v[166:169], v[10:13]
	v_mfma_f32_16x16x32_bf16 v[6:9], v[130:133], v[162:165], v[6:9]
	v_mfma_f32_16x16x32_bf16 v[2:5], v[138:141], v[162:165], v[2:5]
	v_mfma_f32_16x16x32_bf16 v[30:33], v[134:137], v[190:193], v[30:33]
	v_mfma_f32_16x16x32_bf16 v[26:29], v[142:145], v[190:193], v[26:29]
	v_mfma_f32_16x16x32_bf16 v[22:25], v[134:137], v[186:189], v[22:25]
	v_mfma_f32_16x16x32_bf16 v[18:21], v[142:145], v[186:189], v[18:21]
	v_mfma_f32_16x16x32_bf16 v[14:17], v[134:137], v[182:185], v[14:17]
	v_mfma_f32_16x16x32_bf16 v[10:13], v[142:145], v[182:185], v[10:13]
	v_mfma_f32_16x16x32_bf16 v[6:9], v[134:137], v[178:181], v[6:9]
	v_mfma_f32_16x16x32_bf16 v[2:5], v[142:145], v[178:181], v[2:5]
.LBB0_907:
	s_and_b64 vcc, s[40:41], s[72:73]
	v_cndmask_b32_e64 v131, v209, 0, vcc
	v_cndmask_b32_e32 v130, v208, v198, vcc
	v_lshl_add_u64 v[234:235], s[70:71], 0, v[130:131]
	s_barrier
	s_mov_b32 m0, s8
	s_add_u32 vcc_lo, s68, 0x4000
	s_addc_u32 vcc_hi, s69, 0
	s_mov_b32 m0, s11
	s_nop 0
	global_load_lds_dwordx4 v194, vcc
	s_mov_b32 m0, s12
	s_nop 0
	global_load_lds_dwordx4 v196, vcc
	s_mov_b32 m0, s8
	s_nop 0
	global_load_lds_dwordx4 v194, s[98:99]
	s_mov_b32 m0, s13
	s_nop 0
	global_load_lds_dwordx4 v196, s[98:99]
	v_add_u32_e32 v130, 0x18000, v224
	v_add_u32_e32 v142, 0x1c000, v224
	ds_read_b128 v[146:149], v130
	ds_read_b128 v[150:153], v130 offset:1024
	ds_read_b128 v[154:157], v130 offset:2048
	ds_read_b128 v[158:161], v130 offset:3072
	ds_read_b128 v[130:133], v142
	ds_read_b128 v[134:137], v142 offset:1024
	ds_read_b128 v[138:141], v142 offset:2048
	ds_read_b128 v[142:145], v142 offset:3072
	s_mov_b32 m0, s14
	v_lshl_add_u64 v[236:237], v[234:235], 0, v[194:195]
	s_waitcnt lgkmcnt(0)
	ds_read_b128 v[174:177], v228 offset:32768
	ds_read_b128 v[190:193], v228 offset:33792
	ds_read_b128 v[170:173], v228 offset:34816
	ds_read_b128 v[186:189], v228 offset:35840
	ds_read_b128 v[166:169], v228 offset:36864
	ds_read_b128 v[182:185], v228 offset:37888
	ds_read_b128 v[162:165], v228 offset:38912
	ds_read_b128 v[178:181], v228 offset:39936
	global_load_lds_dwordx4 v[236:237], off
	v_lshl_add_u64 v[234:235], v[234:235], 0, v[196:197]
	s_mov_b32 m0, s15
	s_nop 0
	global_load_lds_dwordx4 v[234:235], off
	s_waitcnt vmcnt(8) lgkmcnt(0)
	s_barrier
	v_mfma_f32_16x16x32_bf16 v[126:129], v[146:149], v[174:177], v[126:129]
	v_mfma_f32_16x16x32_bf16 v[122:125], v[154:157], v[174:177], v[122:125]
	v_mfma_f32_16x16x32_bf16 v[118:121], v[146:149], v[170:173], v[118:121]
	v_mfma_f32_16x16x32_bf16 v[114:117], v[154:157], v[170:173], v[114:117]
	v_mfma_f32_16x16x32_bf16 v[110:113], v[146:149], v[166:169], v[110:113]
	v_mfma_f32_16x16x32_bf16 v[106:109], v[154:157], v[166:169], v[106:109]
	v_mfma_f32_16x16x32_bf16 v[102:105], v[146:149], v[162:165], v[102:105]
	v_mfma_f32_16x16x32_bf16 v[98:101], v[154:157], v[162:165], v[98:101]
	v_mfma_f32_16x16x32_bf16 v[126:129], v[150:153], v[190:193], v[126:129]
	v_mfma_f32_16x16x32_bf16 v[122:125], v[158:161], v[190:193], v[122:125]
	v_mfma_f32_16x16x32_bf16 v[118:121], v[150:153], v[186:189], v[118:121]
	v_mfma_f32_16x16x32_bf16 v[114:117], v[158:161], v[186:189], v[114:117]
	v_mfma_f32_16x16x32_bf16 v[110:113], v[150:153], v[182:185], v[110:113]
	v_mfma_f32_16x16x32_bf16 v[106:109], v[158:161], v[182:185], v[106:109]
	v_mfma_f32_16x16x32_bf16 v[102:105], v[150:153], v[178:181], v[102:105]
	v_mfma_f32_16x16x32_bf16 v[98:101], v[158:161], v[178:181], v[98:101]
	v_mfma_f32_16x16x32_bf16 v[94:97], v[130:133], v[174:177], v[94:97]
	v_mfma_f32_16x16x32_bf16 v[90:93], v[138:141], v[174:177], v[90:93]
	v_mfma_f32_16x16x32_bf16 v[86:89], v[130:133], v[170:173], v[86:89]
	v_mfma_f32_16x16x32_bf16 v[82:85], v[138:141], v[170:173], v[82:85]
	v_mfma_f32_16x16x32_bf16 v[78:81], v[130:133], v[166:169], v[78:81]
	v_mfma_f32_16x16x32_bf16 v[74:77], v[138:141], v[166:169], v[74:77]
	v_mfma_f32_16x16x32_bf16 v[70:73], v[130:133], v[162:165], v[70:73]
	v_mfma_f32_16x16x32_bf16 v[66:69], v[138:141], v[162:165], v[66:69]
	v_mfma_f32_16x16x32_bf16 v[94:97], v[134:137], v[190:193], v[94:97]
	v_mfma_f32_16x16x32_bf16 v[90:93], v[142:145], v[190:193], v[90:93]
	v_mfma_f32_16x16x32_bf16 v[86:89], v[134:137], v[186:189], v[86:89]
	v_mfma_f32_16x16x32_bf16 v[82:85], v[142:145], v[186:189], v[82:85]
	v_mfma_f32_16x16x32_bf16 v[78:81], v[134:137], v[182:185], v[78:81]
	v_mfma_f32_16x16x32_bf16 v[74:77], v[142:145], v[182:185], v[74:77]
	v_mfma_f32_16x16x32_bf16 v[70:73], v[134:137], v[178:181], v[70:73]
	v_mfma_f32_16x16x32_bf16 v[66:69], v[142:145], v[178:181], v[66:69]
	s_barrier
	s_and_b64 vcc, exec, s[42:43]
	s_cbranch_vccnz .LBB0_909
	ds_read_b128 v[174:177], v228 offset:49152
	ds_read_b128 v[190:193], v228 offset:50176
	ds_read_b128 v[170:173], v228 offset:51200
	ds_read_b128 v[186:189], v228 offset:52224
	ds_read_b128 v[166:169], v228 offset:53248
	ds_read_b128 v[182:185], v228 offset:54272
	ds_read_b128 v[162:165], v228 offset:55296
	ds_read_b128 v[178:181], v228 offset:56320

.LBB0_1291:
	s_add_u32 s52, s36, s48
	s_addc_u32 s53, s37, s49
	s_add_u32 s56, s52, 0x440000
	s_addc_u32 s57, s53, 0
	s_cmp_eq_u32 s48, 0x3fc0000
	s_cselect_b64 s[58:59], -1, 0
	s_and_b64 s[52:53], s[58:59], exec
	s_cselect_b32 s53, s31, s63
	s_cselect_b32 s52, s61, s62
	s_mov_b32 m0, s9
	s_cselect_b32 s57, s19, s57
	s_cselect_b32 s56, s29, s56
	s_add_u32 s68, s52, 0x4000
	global_load_lds_dwordx4 v194, s[52:53]
	s_mov_b32 m0, s10
	s_addc_u32 s69, s53, 0
	global_load_lds_dwordx4 v196, s[52:53]
	s_and_b64 vcc, exec, s[42:43]
	s_nop 0
	s_mov_b64 s[98:99], s[56:57]
	s_waitcnt vmcnt(4) lgkmcnt(0)
	s_barrier
	s_cbranch_vccnz .LBB0_1293
	s_waitcnt lgkmcnt(0)
	v_mfma_f32_16x16x32_bf16 v[62:65], v[146:149], v[174:177], v[62:65]
	v_mfma_f32_16x16x32_bf16 v[58:61], v[154:157], v[174:177], v[58:61]
	v_mfma_f32_16x16x32_bf16 v[46:49], v[146:149], v[170:173], v[46:49]
	v_mfma_f32_16x16x32_bf16 v[42:45], v[154:157], v[170:173], v[42:45]
	v_mfma_f32_16x16x32_bf16 v[30:33], v[146:149], v[166:169], v[30:33]
	v_mfma_f32_16x16x32_bf16 v[26:29], v[154:157], v[166:169], v[26:29]
	v_mfma_f32_16x16x32_bf16 v[14:17], v[146:149], v[162:165], v[14:17]
	v_mfma_f32_16x16x32_bf16 v[10:13], v[154:157], v[162:165], v[10:13]
	v_mfma_f32_16x16x32_bf16 v[62:65], v[150:153], v[190:193], v[62:65]
	v_mfma_f32_16x16x32_bf16 v[58:61], v[158:161], v[190:193], v[58:61]
	v_mfma_f32_16x16x32_bf16 v[46:49], v[150:153], v[186:189], v[46:49]
	v_mfma_f32_16x16x32_bf16 v[42:45], v[158:161], v[186:189], v[42:45]
	v_mfma_f32_16x16x32_bf16 v[30:33], v[150:153], v[182:185], v[30:33]
	v_mfma_f32_16x16x32_bf16 v[26:29], v[158:161], v[182:185], v[26:29]
	v_mfma_f32_16x16x32_bf16 v[14:17], v[150:153], v[178:181], v[14:17]
	v_mfma_f32_16x16x32_bf16 v[10:13], v[158:161], v[178:181], v[10:13]
	v_mfma_f32_16x16x32_bf16 v[54:57], v[130:133], v[174:177], v[54:57]
	v_mfma_f32_16x16x32_bf16 v[50:53], v[138:141], v[174:177], v[50:53]
	v_mfma_f32_16x16x32_bf16 v[38:41], v[130:133], v[170:173], v[38:41]
	v_mfma_f32_16x16x32_bf16 v[34:37], v[138:141], v[170:173], v[34:37]
	v_mfma_f32_16x16x32_bf16 v[22:25], v[130:133], v[166:169], v[22:25]
	v_mfma_f32_16x16x32_bf16 v[18:21], v[138:141], v[166:169], v[18:21]
	v_mfma_f32_16x16x32_bf16 v[6:9], v[130:133], v[162:165], v[6:9]
	v_mfma_f32_16x16x32_bf16 v[2:5], v[138:141], v[162:165], v[2:5]
	v_mfma_f32_16x16x32_bf16 v[54:57], v[134:137], v[190:193], v[54:57]
	v_mfma_f32_16x16x32_bf16 v[50:53], v[142:145], v[190:193], v[50:53]
	v_mfma_f32_16x16x32_bf16 v[38:41], v[134:137], v[186:189], v[38:41]
	v_mfma_f32_16x16x32_bf16 v[34:37], v[142:145], v[186:189], v[34:37]
	v_mfma_f32_16x16x32_bf16 v[22:25], v[134:137], v[182:185], v[22:25]
	v_mfma_f32_16x16x32_bf16 v[18:21], v[142:145], v[182:185], v[18:21]
	v_mfma_f32_16x16x32_bf16 v[6:9], v[134:137], v[178:181], v[6:9]
	v_mfma_f32_16x16x32_bf16 v[2:5], v[142:145], v[178:181], v[2:5]
.LBB0_1293:
	s_and_b64 vcc, s[34:35], s[58:59]
	v_cndmask_b32_e64 v131, v221, 0, vcc
	v_cndmask_b32_e32 v130, v220, v198, vcc
	v_lshl_add_u64 v[234:235], s[56:57], 0, v[130:131]
	s_barrier
	s_mov_b32 m0, s8
	s_add_u32 vcc_lo, s52, 0x4000
	s_addc_u32 vcc_hi, s53, 0
	s_mov_b32 m0, s11
	s_nop 0
	global_load_lds_dwordx4 v194, vcc
	s_mov_b32 m0, s12
	s_nop 0
	global_load_lds_dwordx4 v196, vcc
	s_mov_b32 m0, s8
	s_nop 0
	global_load_lds_dwordx4 v194, s[98:99]
	s_mov_b32 m0, s13
	s_nop 0
	global_load_lds_dwordx4 v196, s[98:99]
	v_add_u32_e32 v130, 0x18000, v229
	v_add_u32_e32 v142, 0x1c000, v229
	ds_read_b128 v[146:149], v130
	ds_read_b128 v[150:153], v130 offset:1024
	ds_read_b128 v[154:157], v130 offset:2048
	ds_read_b128 v[158:161], v130 offset:3072
	ds_read_b128 v[130:133], v142
	ds_read_b128 v[134:137], v142 offset:1024
	ds_read_b128 v[138:141], v142 offset:2048
	ds_read_b128 v[142:145], v142 offset:3072
	s_mov_b32 m0, s14
	v_lshl_add_u64 v[236:237], v[234:235], 0, v[194:195]
	s_waitcnt lgkmcnt(0)
	ds_read_b128 v[174:177], v231 offset:32768
	ds_read_b128 v[190:193], v231 offset:33792
	ds_read_b128 v[170:173], v231 offset:34816
	ds_read_b128 v[186:189], v231 offset:35840
	ds_read_b128 v[166:169], v231 offset:36864
	ds_read_b128 v[182:185], v231 offset:37888
	ds_read_b128 v[162:165], v231 offset:38912
	ds_read_b128 v[178:181], v231 offset:39936
	global_load_lds_dwordx4 v[236:237], off
	v_lshl_add_u64 v[234:235], v[234:235], 0, v[196:197]
	s_mov_b32 m0, s15
	s_nop 0
	global_load_lds_dwordx4 v[234:235], off
	s_waitcnt vmcnt(8) lgkmcnt(0)
	s_barrier
	v_mfma_f32_16x16x32_bf16 v[126:129], v[146:149], v[174:177], v[126:129]
	v_mfma_f32_16x16x32_bf16 v[122:125], v[154:157], v[174:177], v[122:125]
	v_mfma_f32_16x16x32_bf16 v[118:121], v[146:149], v[170:173], v[118:121]
	v_mfma_f32_16x16x32_bf16 v[110:113], v[154:157], v[170:173], v[110:113]
	v_mfma_f32_16x16x32_bf16 v[102:105], v[146:149], v[166:169], v[102:105]
	v_mfma_f32_16x16x32_bf16 v[94:97], v[154:157], v[166:169], v[94:97]
	v_mfma_f32_16x16x32_bf16 v[86:89], v[146:149], v[162:165], v[86:89]
	v_mfma_f32_16x16x32_bf16 v[78:81], v[154:157], v[162:165], v[78:81]
	v_mfma_f32_16x16x32_bf16 v[126:129], v[150:153], v[190:193], v[126:129]
	v_mfma_f32_16x16x32_bf16 v[122:125], v[158:161], v[190:193], v[122:125]
	v_mfma_f32_16x16x32_bf16 v[118:121], v[150:153], v[186:189], v[118:121]
	v_mfma_f32_16x16x32_bf16 v[110:113], v[158:161], v[186:189], v[110:113]
	v_mfma_f32_16x16x32_bf16 v[102:105], v[150:153], v[182:185], v[102:105]
	v_mfma_f32_16x16x32_bf16 v[94:97], v[158:161], v[182:185], v[94:97]
	v_mfma_f32_16x16x32_bf16 v[86:89], v[150:153], v[178:181], v[86:89]
	v_mfma_f32_16x16x32_bf16 v[78:81], v[158:161], v[178:181], v[78:81]
	v_mfma_f32_16x16x32_bf16 v[114:117], v[130:133], v[174:177], v[114:117]
	v_mfma_f32_16x16x32_bf16 v[106:109], v[138:141], v[174:177], v[106:109]
	v_mfma_f32_16x16x32_bf16 v[98:101], v[130:133], v[170:173], v[98:101]
	v_mfma_f32_16x16x32_bf16 v[90:93], v[138:141], v[170:173], v[90:93]
	v_mfma_f32_16x16x32_bf16 v[82:85], v[130:133], v[166:169], v[82:85]
	v_mfma_f32_16x16x32_bf16 v[74:77], v[138:141], v[166:169], v[74:77]
	v_mfma_f32_16x16x32_bf16 v[70:73], v[130:133], v[162:165], v[70:73]
	v_mfma_f32_16x16x32_bf16 v[66:69], v[138:141], v[162:165], v[66:69]
	v_mfma_f32_16x16x32_bf16 v[114:117], v[134:137], v[190:193], v[114:117]
	v_mfma_f32_16x16x32_bf16 v[106:109], v[142:145], v[190:193], v[106:109]
	v_mfma_f32_16x16x32_bf16 v[98:101], v[134:137], v[186:189], v[98:101]
	v_mfma_f32_16x16x32_bf16 v[90:93], v[142:145], v[186:189], v[90:93]
	v_mfma_f32_16x16x32_bf16 v[82:85], v[134:137], v[182:185], v[82:85]
	v_mfma_f32_16x16x32_bf16 v[74:77], v[142:145], v[182:185], v[74:77]
	v_mfma_f32_16x16x32_bf16 v[70:73], v[134:137], v[178:181], v[70:73]
	v_mfma_f32_16x16x32_bf16 v[66:69], v[142:145], v[178:181], v[66:69]
	s_barrier
	s_and_b64 vcc, exec, s[42:43]
	s_cbranch_vccnz .LBB0_1295
	ds_read_b128 v[174:177], v231 offset:49152
	ds_read_b128 v[190:193], v231 offset:50176
	ds_read_b128 v[170:173], v231 offset:51200
	ds_read_b128 v[186:189], v231 offset:52224
	ds_read_b128 v[166:169], v231 offset:53248
	ds_read_b128 v[182:185], v231 offset:54272
	ds_read_b128 v[162:165], v231 offset:55296
	ds_read_b128 v[178:181], v231 offset:56320

.LBB0_1614:
	s_add_u32 s50, s46, s48
	s_addc_u32 s51, s47, s49
	s_add_u32 s52, s50, 0x440000
	s_addc_u32 s53, s51, 0
	s_cmp_eq_u32 s48, 0x3fc0000
	s_cselect_b64 s[56:57], -1, 0
	s_and_b64 s[50:51], s[56:57], exec
	s_cselect_b32 s51, s31, s61
	s_cselect_b32 s50, s35, s60
	s_mov_b32 m0, s10
	s_cselect_b32 s53, s19, s53
	s_cselect_b32 s52, s20, s52
	s_add_u32 s68, s50, 0x4000
	global_load_lds_dwordx4 v194, s[50:51]
	s_mov_b32 m0, s11
	s_addc_u32 s69, s51, 0
	global_load_lds_dwordx4 v196, s[50:51]
	s_and_b64 vcc, exec, s[42:43]
	s_nop 0
	s_mov_b64 s[98:99], s[52:53]
	s_waitcnt vmcnt(4) lgkmcnt(0)
	s_barrier
	s_cbranch_vccnz .LBB0_1616
	s_waitcnt lgkmcnt(0)
	v_mfma_f32_16x16x32_bf16 v[62:65], v[146:149], v[174:177], v[62:65]
	v_mfma_f32_16x16x32_bf16 v[58:61], v[154:157], v[174:177], v[58:61]
	v_mfma_f32_16x16x32_bf16 v[46:49], v[146:149], v[170:173], v[46:49]
	v_mfma_f32_16x16x32_bf16 v[42:45], v[154:157], v[170:173], v[42:45]
	v_mfma_f32_16x16x32_bf16 v[30:33], v[146:149], v[166:169], v[30:33]
	v_mfma_f32_16x16x32_bf16 v[26:29], v[154:157], v[166:169], v[26:29]
	v_mfma_f32_16x16x32_bf16 v[14:17], v[146:149], v[162:165], v[14:17]
	v_mfma_f32_16x16x32_bf16 v[10:13], v[154:157], v[162:165], v[10:13]
	v_mfma_f32_16x16x32_bf16 v[62:65], v[150:153], v[190:193], v[62:65]
	v_mfma_f32_16x16x32_bf16 v[58:61], v[158:161], v[190:193], v[58:61]
	v_mfma_f32_16x16x32_bf16 v[46:49], v[150:153], v[186:189], v[46:49]
	v_mfma_f32_16x16x32_bf16 v[42:45], v[158:161], v[186:189], v[42:45]
	v_mfma_f32_16x16x32_bf16 v[30:33], v[150:153], v[182:185], v[30:33]
	v_mfma_f32_16x16x32_bf16 v[26:29], v[158:161], v[182:185], v[26:29]
	v_mfma_f32_16x16x32_bf16 v[14:17], v[150:153], v[178:181], v[14:17]
	v_mfma_f32_16x16x32_bf16 v[10:13], v[158:161], v[178:181], v[10:13]
	v_mfma_f32_16x16x32_bf16 v[54:57], v[130:133], v[174:177], v[54:57]
	v_mfma_f32_16x16x32_bf16 v[50:53], v[138:141], v[174:177], v[50:53]
	v_mfma_f32_16x16x32_bf16 v[38:41], v[130:133], v[170:173], v[38:41]
	v_mfma_f32_16x16x32_bf16 v[34:37], v[138:141], v[170:173], v[34:37]
	v_mfma_f32_16x16x32_bf16 v[22:25], v[130:133], v[166:169], v[22:25]
	v_mfma_f32_16x16x32_bf16 v[18:21], v[138:141], v[166:169], v[18:21]
	v_mfma_f32_16x16x32_bf16 v[6:9], v[130:133], v[162:165], v[6:9]
	v_mfma_f32_16x16x32_bf16 v[2:5], v[138:141], v[162:165], v[2:5]
	v_mfma_f32_16x16x32_bf16 v[54:57], v[134:137], v[190:193], v[54:57]
	v_mfma_f32_16x16x32_bf16 v[50:53], v[142:145], v[190:193], v[50:53]
	v_mfma_f32_16x16x32_bf16 v[38:41], v[134:137], v[186:189], v[38:41]
	v_mfma_f32_16x16x32_bf16 v[34:37], v[142:145], v[186:189], v[34:37]
	v_mfma_f32_16x16x32_bf16 v[22:25], v[134:137], v[182:185], v[22:25]
	v_mfma_f32_16x16x32_bf16 v[18:21], v[142:145], v[182:185], v[18:21]
	v_mfma_f32_16x16x32_bf16 v[6:9], v[134:137], v[178:181], v[6:9]
	v_mfma_f32_16x16x32_bf16 v[2:5], v[142:145], v[178:181], v[2:5]
.LBB0_1616:
	s_and_b64 vcc, s[38:39], s[56:57]
	v_cndmask_b32_e64 v131, v225, 0, vcc
	v_cndmask_b32_e32 v130, v224, v198, vcc
	v_lshl_add_u64 v[236:237], s[52:53], 0, v[130:131]
	s_barrier
	s_mov_b32 m0, s9
	s_add_u32 vcc_lo, s50, 0x4000
	s_addc_u32 vcc_hi, s51, 0
	s_mov_b32 m0, s12
	s_nop 0
	global_load_lds_dwordx4 v194, vcc
	s_mov_b32 m0, s13
	s_nop 0
	global_load_lds_dwordx4 v196, vcc
	s_mov_b32 m0, s9
	s_nop 0
	global_load_lds_dwordx4 v194, s[98:99]
	s_mov_b32 m0, s14
	s_nop 0
	global_load_lds_dwordx4 v196, s[98:99]
	v_add_u32_e32 v1, 0x18000, v232
	ds_read_b128 v[146:149], v1
	ds_read_b128 v[150:153], v1 offset:1024
	ds_read_b128 v[154:157], v1 offset:2048
	ds_read_b128 v[158:161], v1 offset:3072
	v_add_u32_e32 v1, 0x1c000, v232
	ds_read_b128 v[130:133], v1
	ds_read_b128 v[134:137], v1 offset:1024
	ds_read_b128 v[138:141], v1 offset:2048
	ds_read_b128 v[142:145], v1 offset:3072
	s_mov_b32 m0, s15
	v_lshl_add_u64 v[238:239], v[236:237], 0, v[194:195]
	s_waitcnt lgkmcnt(0)
	ds_read_b128 v[174:177], v233 offset:32768
	ds_read_b128 v[190:193], v233 offset:33792
	ds_read_b128 v[170:173], v233 offset:34816
	ds_read_b128 v[186:189], v233 offset:35840
	ds_read_b128 v[166:169], v233 offset:36864
	ds_read_b128 v[182:185], v233 offset:37888
	ds_read_b128 v[162:165], v233 offset:38912
	ds_read_b128 v[178:181], v233 offset:39936
	global_load_lds_dwordx4 v[238:239], off
	v_lshl_add_u64 v[236:237], v[236:237], 0, v[196:197]
	s_mov_b32 m0, s16
	s_nop 0
	global_load_lds_dwordx4 v[236:237], off
	s_waitcnt vmcnt(8) lgkmcnt(0)
	s_barrier
	v_mfma_f32_16x16x32_bf16 v[126:129], v[146:149], v[174:177], v[126:129]
	v_mfma_f32_16x16x32_bf16 v[122:125], v[154:157], v[174:177], v[122:125]
	v_mfma_f32_16x16x32_bf16 v[118:121], v[146:149], v[170:173], v[118:121]
	v_mfma_f32_16x16x32_bf16 v[110:113], v[154:157], v[170:173], v[110:113]
	v_mfma_f32_16x16x32_bf16 v[102:105], v[146:149], v[166:169], v[102:105]
	v_mfma_f32_16x16x32_bf16 v[94:97], v[154:157], v[166:169], v[94:97]
	v_mfma_f32_16x16x32_bf16 v[86:89], v[146:149], v[162:165], v[86:89]
	v_mfma_f32_16x16x32_bf16 v[78:81], v[154:157], v[162:165], v[78:81]
	v_mfma_f32_16x16x32_bf16 v[126:129], v[150:153], v[190:193], v[126:129]
	v_mfma_f32_16x16x32_bf16 v[122:125], v[158:161], v[190:193], v[122:125]
	v_mfma_f32_16x16x32_bf16 v[118:121], v[150:153], v[186:189], v[118:121]
	v_mfma_f32_16x16x32_bf16 v[110:113], v[158:161], v[186:189], v[110:113]
	v_mfma_f32_16x16x32_bf16 v[102:105], v[150:153], v[182:185], v[102:105]
	v_mfma_f32_16x16x32_bf16 v[94:97], v[158:161], v[182:185], v[94:97]
	v_mfma_f32_16x16x32_bf16 v[86:89], v[150:153], v[178:181], v[86:89]
	v_mfma_f32_16x16x32_bf16 v[78:81], v[158:161], v[178:181], v[78:81]
	v_mfma_f32_16x16x32_bf16 v[114:117], v[130:133], v[174:177], v[114:117]
	v_mfma_f32_16x16x32_bf16 v[106:109], v[138:141], v[174:177], v[106:109]
	v_mfma_f32_16x16x32_bf16 v[98:101], v[130:133], v[170:173], v[98:101]
	v_mfma_f32_16x16x32_bf16 v[90:93], v[138:141], v[170:173], v[90:93]
	v_mfma_f32_16x16x32_bf16 v[82:85], v[130:133], v[166:169], v[82:85]
	v_mfma_f32_16x16x32_bf16 v[74:77], v[138:141], v[166:169], v[74:77]
	v_mfma_f32_16x16x32_bf16 v[70:73], v[130:133], v[162:165], v[70:73]
	v_mfma_f32_16x16x32_bf16 v[66:69], v[138:141], v[162:165], v[66:69]
	v_mfma_f32_16x16x32_bf16 v[114:117], v[134:137], v[190:193], v[114:117]
	v_mfma_f32_16x16x32_bf16 v[106:109], v[142:145], v[190:193], v[106:109]
	v_mfma_f32_16x16x32_bf16 v[98:101], v[134:137], v[186:189], v[98:101]
	v_mfma_f32_16x16x32_bf16 v[90:93], v[142:145], v[186:189], v[90:93]
	v_mfma_f32_16x16x32_bf16 v[82:85], v[134:137], v[182:185], v[82:85]
	v_mfma_f32_16x16x32_bf16 v[74:77], v[142:145], v[182:185], v[74:77]
	v_mfma_f32_16x16x32_bf16 v[70:73], v[134:137], v[178:181], v[70:73]
	v_mfma_f32_16x16x32_bf16 v[66:69], v[142:145], v[178:181], v[66:69]
	s_barrier
	s_and_b64 vcc, exec, s[42:43]
	s_cbranch_vccnz .LBB0_1618
	ds_read_b128 v[174:177], v233 offset:49152
	ds_read_b128 v[190:193], v233 offset:50176
	ds_read_b128 v[170:173], v233 offset:51200
	ds_read_b128 v[186:189], v233 offset:52224
	ds_read_b128 v[166:169], v233 offset:53248
	ds_read_b128 v[182:185], v233 offset:54272
	ds_read_b128 v[162:165], v233 offset:55296
	ds_read_b128 v[178:181], v233 offset:56320
